# qsfold: rotary in-proj epilogue with the power-of-two q scale folded into the row scale (bit-identical, 64 packed multiplies fewer per rotary tile); on top of v90
# baseline (speedup 1.0000x reference)
; #define GAS __attribute__((address_space(1)))
;     __device__ __forceinline__ void operator()(const f32x4 (&acc)[2][2][4][2], const Unit& u, int wr, int wc, int fr, int fq, const PG8_LAS float* tab) const {
;         const int pn = u.pn; const bool is_rope = (pn < 4) || (pn == 8); const bool is_z = (pn >= 18); const float qs = (pn < 4) ? 0.125f : 1.0f;
; #pragma unroll
;         for (int ai = 0; ai < 2; ++ai)
; #pragma unroll
;             for (int m = 0; m < 4; ++m) {
;                 const int row = u.pm * BM + ai * HALF + wr * 64 + m * 16 + fr;
;                 const float rs = rsqrtf(tab[ai * HALF + wr * 64 + m * 16 + fr] * (1.0f / 2048.0f) + 1e-6f);
;                 const int pos = row < 16384 ? (row & 8191) : (row - 16384);
;                 GAS bf16_t* rowp = (GAS bf16_t*)P + (size_t)row * 5120;
;                 if (is_z) {
;                     const f32x4 z0 = (acc[ai][0][m][0] * rs) * (acc[ai][1][m][0] * rs), z1 = (acc[ai][0][m][1] * rs) * (acc[ai][1][m][1] * rs);
;                     u32x4 w; w.x = cvt_pk_bf16(z0[0], z0[1]); w.y = cvt_pk_bf16(z0[2], z0[3]); w.z = cvt_pk_bf16(z1[0], z1[1]); w.w = cvt_pk_bf16(z1[2], z1[3]);
;                     *(GAS u32x4*)(rowp + 4608 + (pn - 18) * 128 + wc * 32 + 8 * fq) = w;
;                     continue;
;                 }
; #pragma unroll
;                 for (int bj = 0; bj < 2; ++bj) {
;                     const int col0 = pn * BM + bj * HALF + wc * 32 + 8 * fq;
;                     f32x4 v0 = acc[ai][bj][m][0] * rs, v1 = acc[ai][bj][m][1] * rs;
;                     if (is_rope) {
;                         const GAS f32x4* rp = (const GAS f32x4*)((const GAS f32x2*)rope + (size_t)pos * 32 + ((col0 & 63) >> 1));
;                         const f32x4 cs0 = rp[0], cs1 = rp[1];
;                         f32x4 o0, o1;
;                         o0[0] = v0[0] * cs0[0] - v0[1] * cs0[1]; o0[1] = v0[1] * cs0[0] + v0[0] * cs0[1];
;                         o0[2] = v0[2] * cs0[2] - v0[3] * cs0[3]; o0[3] = v0[3] * cs0[2] + v0[2] * cs0[3];
;                         o1[0] = v1[0] * cs1[0] - v1[1] * cs1[1]; o1[1] = v1[1] * cs1[0] + v1[0] * cs1[1];
;                         o1[2] = v1[2] * cs1[2] - v1[3] * cs1[3]; o1[3] = v1[3] * cs1[2] + v1[2] * cs1[3];
;                         v0 = o0 * qs; v1 = o1 * qs;
;                     }
;                     {
.Lei_rope:
	s_and_b32 s4, s3, 1
	s_lshl_b32 s4, s4, 10
	v_add_u32_e32 v231, s4, v172
	ds_read_b32 v154, v231 offset:0
	ds_read_b32 v156, v231 offset:64
	ds_read_b32 v158, v231 offset:128
	ds_read_b32 v160, v231 offset:192
	ds_read_b32 v155, v231 offset:512
	ds_read_b32 v157, v231 offset:576
	ds_read_b32 v159, v231 offset:640
	ds_read_b32 v161, v231 offset:704
	s_cmp_lt_i32 s0, 4
	s_cselect_b32 s4, 0x3e000000, 1.0
	v_mov_b32_e32 v234, s4
	v_mov_b32_e32 v235, s4
	s_cmp_lt_i32 s1, 64
	s_cselect_b32 s4, 31, 63
	s_and_b32 s4, s1, s4
	s_lshl_b32 s4, s4, 16
	s_add_u32 s28, s14, s4
	s_addc_u32 s29, s15, 0
	v_lshlrev_b32_e32 v232, 2, v173
	v_and_b32_e32 v232, 0xe0, v232
	v_lshl_add_u32 v232, v1, 8, v232
	s_mov_b64 s[10:11], s[28:29]
	global_load_dwordx4 v[176:179], v232, s[10:11]
	global_load_dwordx4 v[180:183], v232, s[10:11] offset:16
	s_add_u32 s10, s28, 0x1000
	s_addc_u32 s11, s29, 0
	global_load_dwordx4 v[184:187], v232, s[10:11]
	global_load_dwordx4 v[188:191], v232, s[10:11] offset:16
	s_add_u32 s10, s28, 0x2000
	s_addc_u32 s11, s29, 0
	global_load_dwordx4 v[192:195], v232, s[10:11]
	global_load_dwordx4 v[196:199], v232, s[10:11] offset:16
	s_add_u32 s10, s28, 0x3000
	s_addc_u32 s11, s29, 0
	global_load_dwordx4 v[200:203], v232, s[10:11]
	global_load_dwordx4 v[204:207], v232, s[10:11] offset:16
	s_add_u32 s10, s28, 0x8000
	s_addc_u32 s11, s29, 0
	global_load_dwordx4 v[208:211], v232, s[10:11]
	global_load_dwordx4 v[212:215], v232, s[10:11] offset:16
	s_add_u32 s10, s28, 0x9000
	s_addc_u32 s11, s29, 0
	global_load_dwordx4 v[216:219], v232, s[10:11]
	global_load_dwordx4 v[220:223], v232, s[10:11] offset:16
	s_add_u32 s10, s28, 0xa000
	s_addc_u32 s11, s29, 0
	global_load_dwordx4 v[224:227], v232, s[10:11]
	global_load_dwordx4 v[240:243], v232, s[10:11] offset:16
	s_add_u32 s10, s28, 0xb000
	s_addc_u32 s11, s29, 0
	global_load_dwordx4 v[244:247], v232, s[10:11]
	global_load_dwordx4 v[248:251], v232, s[10:11] offset:16
	s_mul_i32 s4, s1, 0x280000
	s_lshl_b32 s5, s0, 9
	s_add_u32 s4, s4, s5
	s_add_u32 s6, s86, s4
	s_addc_u32 s7, s87, 0
	v_mul_u32_u24_e32 v230, 0x2800, v1
	v_lshl_add_u32 v230, v173, 1, v230
	s_waitcnt lgkmcnt(0)
	v_fmamk_f32 v154, v154, 0x3a000000, v236
	v_fmamk_f32 v156, v156, 0x3a000000, v236
	v_fmamk_f32 v158, v158, 0x3a000000, v236
	v_fmamk_f32 v160, v160, 0x3a000000, v236
	v_fmamk_f32 v155, v155, 0x3a000000, v236
	v_fmamk_f32 v157, v157, 0x3a000000, v236
	v_fmamk_f32 v159, v159, 0x3a000000, v236
	v_fmamk_f32 v161, v161, 0x3a000000, v236
	v_rsq_f32_e32 v154, v154
	v_rsq_f32_e32 v156, v156
	v_rsq_f32_e32 v158, v158
	v_rsq_f32_e32 v160, v160
	v_rsq_f32_e32 v155, v155
	v_rsq_f32_e32 v157, v157
	v_rsq_f32_e32 v159, v159
	v_rsq_f32_e32 v161, v161
	v_mul_f32_e32 v154, v234, v154
	v_mul_f32_e32 v156, v234, v156
	v_mul_f32_e32 v158, v234, v158
	v_mul_f32_e32 v160, v234, v160
	v_mul_f32_e32 v155, v234, v155
	v_mul_f32_e32 v157, v234, v157
	v_mul_f32_e32 v159, v234, v159
	v_mul_f32_e32 v161, v234, v161
	s_mov_b64 s[10:11], s[6:7]
	v_pk_mul_f32 v[126:127], v[126:127], v[154:155] op_sel_hi:[1,0]
	v_pk_mul_f32 v[128:129], v[128:129], v[154:155] op_sel_hi:[1,0]
	v_pk_mul_f32 v[122:123], v[122:123], v[154:155] op_sel_hi:[1,0]
	v_pk_mul_f32 v[124:125], v[124:125], v[154:155] op_sel_hi:[1,0]
	v_pk_mul_f32 v[118:119], v[118:119], v[154:155] op_sel_hi:[1,0]
	v_pk_mul_f32 v[120:121], v[120:121], v[154:155] op_sel_hi:[1,0]
	v_pk_mul_f32 v[114:115], v[114:115], v[154:155] op_sel_hi:[1,0]
	v_pk_mul_f32 v[116:117], v[116:117], v[154:155] op_sel_hi:[1,0]
	s_waitcnt vmcnt(14)
	v_pk_mul_f32 v[162:163], v[126:127], v[176:177] op_sel:[1,1] op_sel_hi:[0,1]
	v_pk_fma_f32 v[126:127], v[126:127], v[176:177], v[162:163] op_sel_hi:[1,0,1] neg_lo:[0,0,1]
	v_pk_mul_f32 v[162:163], v[128:129], v[178:179] op_sel:[1,1] op_sel_hi:[0,1]
	v_pk_fma_f32 v[128:129], v[128:129], v[178:179], v[162:163] op_sel_hi:[1,0,1] neg_lo:[0,0,1]
	v_pk_mul_f32 v[162:163], v[122:123], v[180:181] op_sel:[1,1] op_sel_hi:[0,1]
	v_pk_fma_f32 v[122:123], v[122:123], v[180:181], v[162:163] op_sel_hi:[1,0,1] neg_lo:[0,0,1]
	v_pk_mul_f32 v[162:163], v[124:125], v[182:183] op_sel:[1,1] op_sel_hi:[0,1]
	v_pk_fma_f32 v[124:125], v[124:125], v[182:183], v[162:163] op_sel_hi:[1,0,1] neg_lo:[0,0,1]
	v_cvt_pk_bf16_f32 v164, v126, v127
	v_cvt_pk_bf16_f32 v165, v128, v129
	v_cvt_pk_bf16_f32 v166, v122, v123
	v_cvt_pk_bf16_f32 v167, v124, v125
	global_store_dwordx4 v230, v[164:167], s[10:11] offset:0
	v_pk_mul_f32 v[162:163], v[118:119], v[176:177] op_sel:[1,1] op_sel_hi:[0,1]
	v_pk_fma_f32 v[118:119], v[118:119], v[176:177], v[162:163] op_sel_hi:[1,0,1] neg_lo:[0,0,1]
	v_pk_mul_f32 v[162:163], v[120:121], v[178:179] op_sel:[1,1] op_sel_hi:[0,1]
	v_pk_fma_f32 v[120:121], v[120:121], v[178:179], v[162:163] op_sel_hi:[1,0,1] neg_lo:[0,0,1]
	v_pk_mul_f32 v[162:163], v[114:115], v[180:181] op_sel:[1,1] op_sel_hi:[0,1]
	v_pk_fma_f32 v[114:115], v[114:115], v[180:181], v[162:163] op_sel_hi:[1,0,1] neg_lo:[0,0,1]
	v_pk_mul_f32 v[162:163], v[116:117], v[182:183] op_sel:[1,1] op_sel_hi:[0,1]
	v_pk_fma_f32 v[116:117], v[116:117], v[182:183], v[162:163] op_sel_hi:[1,0,1] neg_lo:[0,0,1]
	v_cvt_pk_bf16_f32 v168, v118, v119
	v_cvt_pk_bf16_f32 v169, v120, v121
	v_cvt_pk_bf16_f32 v170, v114, v115
	v_cvt_pk_bf16_f32 v171, v116, v117
	global_store_dwordx4 v230, v[168:171], s[10:11] offset:256
	s_add_u32 s10, s6, 0x28000
	s_addc_u32 s11, s7, 0
	v_pk_mul_f32 v[110:111], v[110:111], v[156:157] op_sel_hi:[1,0]
	v_pk_mul_f32 v[112:113], v[112:113], v[156:157] op_sel_hi:[1,0]
	v_pk_mul_f32 v[106:107], v[106:107], v[156:157] op_sel_hi:[1,0]
	v_pk_mul_f32 v[108:109], v[108:109], v[156:157] op_sel_hi:[1,0]
	v_pk_mul_f32 v[102:103], v[102:103], v[156:157] op_sel_hi:[1,0]
	v_pk_mul_f32 v[104:105], v[104:105], v[156:157] op_sel_hi:[1,0]
	v_pk_mul_f32 v[98:99], v[98:99], v[156:157] op_sel_hi:[1,0]
	v_pk_mul_f32 v[100:101], v[100:101], v[156:157] op_sel_hi:[1,0]
	s_waitcnt vmcnt(14)
; #define GAS __attribute__((address_space(1)))
; __device__ __forceinline__ unsigned cvt_pk_bf16(float lo, float hi) { unsigned r; asm volatile("v_cvt_pk_bf16_f32 %0, %1, %2" : "=v"(r) : "v"(lo), "v"(hi)); return r; }
;     __device__ __forceinline__ void operator()(const f32x4 (&acc)[2][2][4][2], const Unit& u, int wr, int wc, int fr, int fq, const PG8_LAS float* tab) const {
;     ...
;                     f32x4 v0 = acc[ai][bj][m][0] * rs, v1 = acc[ai][bj][m][1] * rs;
;                     if (is_rope) {
;                         const GAS f32x4* rp = (const GAS f32x4*)((const GAS f32x2*)rope + (size_t)pos * 32 + ((col0 & 63) >> 1));
;                         const f32x4 cs0 = rp[0], cs1 = rp[1];
;                         f32x4 o0, o1;
;                         o0[0] = v0[0] * cs0[0] - v0[1] * cs0[1]; o0[1] = v0[1] * cs0[0] + v0[0] * cs0[1];
;                         o0[2] = v0[2] * cs0[2] - v0[3] * cs0[3]; o0[3] = v0[3] * cs0[2] + v0[2] * cs0[3];
;                         o1[0] = v1[0] * cs1[0] - v1[1] * cs1[1]; o1[1] = v1[1] * cs1[0] + v1[0] * cs1[1];
;                         o1[2] = v1[2] * cs1[2] - v1[3] * cs1[3]; o1[3] = v1[3] * cs1[2] + v1[2] * cs1[3];
;                         v0 = o0 * qs; v1 = o1 * qs;
;                     }
;                     {
;                         u32x4 w; w.x = cvt_pk_bf16(v0[0], v0[1]); w.y = cvt_pk_bf16(v0[2], v0[3]); w.z = cvt_pk_bf16(v1[0], v1[1]); w.w = cvt_pk_bf16(v1[2], v1[3]);
;                         *(GAS u32x4*)(rowp + col0) = w;
	v_pk_mul_f32 v[162:163], v[110:111], v[184:185] op_sel:[1,1] op_sel_hi:[0,1]
	v_pk_fma_f32 v[110:111], v[110:111], v[184:185], v[162:163] op_sel_hi:[1,0,1] neg_lo:[0,0,1]
	v_pk_mul_f32 v[162:163], v[112:113], v[186:187] op_sel:[1,1] op_sel_hi:[0,1]
	v_pk_fma_f32 v[112:113], v[112:113], v[186:187], v[162:163] op_sel_hi:[1,0,1] neg_lo:[0,0,1]
	v_pk_mul_f32 v[162:163], v[106:107], v[188:189] op_sel:[1,1] op_sel_hi:[0,1]
	v_pk_fma_f32 v[106:107], v[106:107], v[188:189], v[162:163] op_sel_hi:[1,0,1] neg_lo:[0,0,1]
	v_pk_mul_f32 v[162:163], v[108:109], v[190:191] op_sel:[1,1] op_sel_hi:[0,1]
	v_pk_fma_f32 v[108:109], v[108:109], v[190:191], v[162:163] op_sel_hi:[1,0,1] neg_lo:[0,0,1]
	v_cvt_pk_bf16_f32 v164, v110, v111
	v_cvt_pk_bf16_f32 v165, v112, v113
	v_cvt_pk_bf16_f32 v166, v106, v107
	v_cvt_pk_bf16_f32 v167, v108, v109
	global_store_dwordx4 v230, v[164:167], s[10:11] offset:0
	v_pk_mul_f32 v[162:163], v[102:103], v[184:185] op_sel:[1,1] op_sel_hi:[0,1]
	v_pk_fma_f32 v[102:103], v[102:103], v[184:185], v[162:163] op_sel_hi:[1,0,1] neg_lo:[0,0,1]
	v_pk_mul_f32 v[162:163], v[104:105], v[186:187] op_sel:[1,1] op_sel_hi:[0,1]
	v_pk_fma_f32 v[104:105], v[104:105], v[186:187], v[162:163] op_sel_hi:[1,0,1] neg_lo:[0,0,1]
	v_pk_mul_f32 v[162:163], v[98:99], v[188:189] op_sel:[1,1] op_sel_hi:[0,1]
	v_pk_fma_f32 v[98:99], v[98:99], v[188:189], v[162:163] op_sel_hi:[1,0,1] neg_lo:[0,0,1]
	v_pk_mul_f32 v[162:163], v[100:101], v[190:191] op_sel:[1,1] op_sel_hi:[0,1]
	v_pk_fma_f32 v[100:101], v[100:101], v[190:191], v[162:163] op_sel_hi:[1,0,1] neg_lo:[0,0,1]
	v_cvt_pk_bf16_f32 v168, v102, v103
	v_cvt_pk_bf16_f32 v169, v104, v105
	v_cvt_pk_bf16_f32 v170, v98, v99
	v_cvt_pk_bf16_f32 v171, v100, v101
	global_store_dwordx4 v230, v[168:171], s[10:11] offset:256
	s_add_u32 s10, s6, 0x50000
	s_addc_u32 s11, s7, 0
	v_pk_mul_f32 v[94:95], v[94:95], v[158:159] op_sel_hi:[1,0]
	v_pk_mul_f32 v[96:97], v[96:97], v[158:159] op_sel_hi:[1,0]
	v_pk_mul_f32 v[90:91], v[90:91], v[158:159] op_sel_hi:[1,0]
	v_pk_mul_f32 v[92:93], v[92:93], v[158:159] op_sel_hi:[1,0]
	v_pk_mul_f32 v[86:87], v[86:87], v[158:159] op_sel_hi:[1,0]
	v_pk_mul_f32 v[88:89], v[88:89], v[158:159] op_sel_hi:[1,0]
	v_pk_mul_f32 v[82:83], v[82:83], v[158:159] op_sel_hi:[1,0]
	v_pk_mul_f32 v[84:85], v[84:85], v[158:159] op_sel_hi:[1,0]
	s_waitcnt vmcnt(14)
	v_pk_mul_f32 v[162:163], v[94:95], v[192:193] op_sel:[1,1] op_sel_hi:[0,1]
	v_pk_fma_f32 v[94:95], v[94:95], v[192:193], v[162:163] op_sel_hi:[1,0,1] neg_lo:[0,0,1]
	v_pk_mul_f32 v[162:163], v[96:97], v[194:195] op_sel:[1,1] op_sel_hi:[0,1]
	v_pk_fma_f32 v[96:97], v[96:97], v[194:195], v[162:163] op_sel_hi:[1,0,1] neg_lo:[0,0,1]
	v_pk_mul_f32 v[162:163], v[90:91], v[196:197] op_sel:[1,1] op_sel_hi:[0,1]
	v_pk_fma_f32 v[90:91], v[90:91], v[196:197], v[162:163] op_sel_hi:[1,0,1] neg_lo:[0,0,1]
	v_pk_mul_f32 v[162:163], v[92:93], v[198:199] op_sel:[1,1] op_sel_hi:[0,1]
	v_pk_fma_f32 v[92:93], v[92:93], v[198:199], v[162:163] op_sel_hi:[1,0,1] neg_lo:[0,0,1]
	v_cvt_pk_bf16_f32 v164, v94, v95
	v_cvt_pk_bf16_f32 v165, v96, v97
	v_cvt_pk_bf16_f32 v166, v90, v91
	v_cvt_pk_bf16_f32 v167, v92, v93
	global_store_dwordx4 v230, v[164:167], s[10:11] offset:0
	v_pk_mul_f32 v[162:163], v[86:87], v[192:193] op_sel:[1,1] op_sel_hi:[0,1]
	v_pk_fma_f32 v[86:87], v[86:87], v[192:193], v[162:163] op_sel_hi:[1,0,1] neg_lo:[0,0,1]
	v_pk_mul_f32 v[162:163], v[88:89], v[194:195] op_sel:[1,1] op_sel_hi:[0,1]
	v_pk_fma_f32 v[88:89], v[88:89], v[194:195], v[162:163] op_sel_hi:[1,0,1] neg_lo:[0,0,1]
	v_pk_mul_f32 v[162:163], v[82:83], v[196:197] op_sel:[1,1] op_sel_hi:[0,1]
	v_pk_fma_f32 v[82:83], v[82:83], v[196:197], v[162:163] op_sel_hi:[1,0,1] neg_lo:[0,0,1]
	v_pk_mul_f32 v[162:163], v[84:85], v[198:199] op_sel:[1,1] op_sel_hi:[0,1]
	v_pk_fma_f32 v[84:85], v[84:85], v[198:199], v[162:163] op_sel_hi:[1,0,1] neg_lo:[0,0,1]
	v_cvt_pk_bf16_f32 v168, v86, v87
	v_cvt_pk_bf16_f32 v169, v88, v89
	v_cvt_pk_bf16_f32 v170, v82, v83
	v_cvt_pk_bf16_f32 v171, v84, v85
	global_store_dwordx4 v230, v[168:171], s[10:11] offset:256
	s_add_u32 s10, s6, 0x78000
	s_addc_u32 s11, s7, 0
	v_pk_mul_f32 v[78:79], v[78:79], v[160:161] op_sel_hi:[1,0]
	v_pk_mul_f32 v[80:81], v[80:81], v[160:161] op_sel_hi:[1,0]
	v_pk_mul_f32 v[74:75], v[74:75], v[160:161] op_sel_hi:[1,0]
	v_pk_mul_f32 v[76:77], v[76:77], v[160:161] op_sel_hi:[1,0]
	v_pk_mul_f32 v[70:71], v[70:71], v[160:161] op_sel_hi:[1,0]
	v_pk_mul_f32 v[72:73], v[72:73], v[160:161] op_sel_hi:[1,0]
	v_pk_mul_f32 v[66:67], v[66:67], v[160:161] op_sel_hi:[1,0]
	v_pk_mul_f32 v[68:69], v[68:69], v[160:161] op_sel_hi:[1,0]
	s_waitcnt vmcnt(14)
; #define GAS __attribute__((address_space(1)))
; __device__ __forceinline__ unsigned cvt_pk_bf16(float lo, float hi) { unsigned r; asm volatile("v_cvt_pk_bf16_f32 %0, %1, %2" : "=v"(r) : "v"(lo), "v"(hi)); return r; }
;     __device__ __forceinline__ void operator()(const f32x4 (&acc)[2][2][4][2], const Unit& u, int wr, int wc, int fr, int fq, const PG8_LAS float* tab) const {
;     ...
;                     f32x4 v0 = acc[ai][bj][m][0] * rs, v1 = acc[ai][bj][m][1] * rs;
;                     if (is_rope) {
;                         const GAS f32x4* rp = (const GAS f32x4*)((const GAS f32x2*)rope + (size_t)pos * 32 + ((col0 & 63) >> 1));
;                         const f32x4 cs0 = rp[0], cs1 = rp[1];
;                         f32x4 o0, o1;
;                         o0[0] = v0[0] * cs0[0] - v0[1] * cs0[1]; o0[1] = v0[1] * cs0[0] + v0[0] * cs0[1];
;                         o0[2] = v0[2] * cs0[2] - v0[3] * cs0[3]; o0[3] = v0[3] * cs0[2] + v0[2] * cs0[3];
;                         o1[0] = v1[0] * cs1[0] - v1[1] * cs1[1]; o1[1] = v1[1] * cs1[0] + v1[0] * cs1[1];
;                         o1[2] = v1[2] * cs1[2] - v1[3] * cs1[3]; o1[3] = v1[3] * cs1[2] + v1[2] * cs1[3];
;                         v0 = o0 * qs; v1 = o1 * qs;
;                     }
;                     {
;                         u32x4 w; w.x = cvt_pk_bf16(v0[0], v0[1]); w.y = cvt_pk_bf16(v0[2], v0[3]); w.z = cvt_pk_bf16(v1[0], v1[1]); w.w = cvt_pk_bf16(v1[2], v1[3]);
;                         *(GAS u32x4*)(rowp + col0) = w;
	v_pk_mul_f32 v[162:163], v[78:79], v[200:201] op_sel:[1,1] op_sel_hi:[0,1]
	v_pk_fma_f32 v[78:79], v[78:79], v[200:201], v[162:163] op_sel_hi:[1,0,1] neg_lo:[0,0,1]
	v_pk_mul_f32 v[162:163], v[80:81], v[202:203] op_sel:[1,1] op_sel_hi:[0,1]
	v_pk_fma_f32 v[80:81], v[80:81], v[202:203], v[162:163] op_sel_hi:[1,0,1] neg_lo:[0,0,1]
	v_pk_mul_f32 v[162:163], v[74:75], v[204:205] op_sel:[1,1] op_sel_hi:[0,1]
	v_pk_fma_f32 v[74:75], v[74:75], v[204:205], v[162:163] op_sel_hi:[1,0,1] neg_lo:[0,0,1]
	v_pk_mul_f32 v[162:163], v[76:77], v[206:207] op_sel:[1,1] op_sel_hi:[0,1]
	v_pk_fma_f32 v[76:77], v[76:77], v[206:207], v[162:163] op_sel_hi:[1,0,1] neg_lo:[0,0,1]
	v_cvt_pk_bf16_f32 v164, v78, v79
	v_cvt_pk_bf16_f32 v165, v80, v81
	v_cvt_pk_bf16_f32 v166, v74, v75
	v_cvt_pk_bf16_f32 v167, v76, v77
	global_store_dwordx4 v230, v[164:167], s[10:11] offset:0
	v_pk_mul_f32 v[162:163], v[70:71], v[200:201] op_sel:[1,1] op_sel_hi:[0,1]
	v_pk_fma_f32 v[70:71], v[70:71], v[200:201], v[162:163] op_sel_hi:[1,0,1] neg_lo:[0,0,1]
	v_pk_mul_f32 v[162:163], v[72:73], v[202:203] op_sel:[1,1] op_sel_hi:[0,1]
	v_pk_fma_f32 v[72:73], v[72:73], v[202:203], v[162:163] op_sel_hi:[1,0,1] neg_lo:[0,0,1]
	v_pk_mul_f32 v[162:163], v[66:67], v[204:205] op_sel:[1,1] op_sel_hi:[0,1]
	v_pk_fma_f32 v[66:67], v[66:67], v[204:205], v[162:163] op_sel_hi:[1,0,1] neg_lo:[0,0,1]
	v_pk_mul_f32 v[162:163], v[68:69], v[206:207] op_sel:[1,1] op_sel_hi:[0,1]
	v_pk_fma_f32 v[68:69], v[68:69], v[206:207], v[162:163] op_sel_hi:[1,0,1] neg_lo:[0,0,1]
	v_cvt_pk_bf16_f32 v168, v70, v71
	v_cvt_pk_bf16_f32 v169, v72, v73
	v_cvt_pk_bf16_f32 v170, v66, v67
	v_cvt_pk_bf16_f32 v171, v68, v69
	global_store_dwordx4 v230, v[168:171], s[10:11] offset:256
	v_mov_b32_e32 v154, v155
	v_mov_b32_e32 v156, v157
	v_mov_b32_e32 v158, v159
	v_mov_b32_e32 v160, v161
	s_add_u32 s10, s6, 0x140000
	s_addc_u32 s11, s7, 0
	v_pk_mul_f32 v[62:63], v[62:63], v[154:155] op_sel_hi:[1,0]
	v_pk_mul_f32 v[64:65], v[64:65], v[154:155] op_sel_hi:[1,0]
	v_pk_mul_f32 v[58:59], v[58:59], v[154:155] op_sel_hi:[1,0]
	v_pk_mul_f32 v[60:61], v[60:61], v[154:155] op_sel_hi:[1,0]
	v_pk_mul_f32 v[54:55], v[54:55], v[154:155] op_sel_hi:[1,0]
	v_pk_mul_f32 v[56:57], v[56:57], v[154:155] op_sel_hi:[1,0]
	v_pk_mul_f32 v[50:51], v[50:51], v[154:155] op_sel_hi:[1,0]
	v_pk_mul_f32 v[52:53], v[52:53], v[154:155] op_sel_hi:[1,0]
	s_waitcnt vmcnt(14)
	v_pk_mul_f32 v[162:163], v[62:63], v[208:209] op_sel:[1,1] op_sel_hi:[0,1]
	v_pk_fma_f32 v[62:63], v[62:63], v[208:209], v[162:163] op_sel_hi:[1,0,1] neg_lo:[0,0,1]
	v_pk_mul_f32 v[162:163], v[64:65], v[210:211] op_sel:[1,1] op_sel_hi:[0,1]
	v_pk_fma_f32 v[64:65], v[64:65], v[210:211], v[162:163] op_sel_hi:[1,0,1] neg_lo:[0,0,1]
	v_pk_mul_f32 v[162:163], v[58:59], v[212:213] op_sel:[1,1] op_sel_hi:[0,1]
	v_pk_fma_f32 v[58:59], v[58:59], v[212:213], v[162:163] op_sel_hi:[1,0,1] neg_lo:[0,0,1]
	v_pk_mul_f32 v[162:163], v[60:61], v[214:215] op_sel:[1,1] op_sel_hi:[0,1]
	v_pk_fma_f32 v[60:61], v[60:61], v[214:215], v[162:163] op_sel_hi:[1,0,1] neg_lo:[0,0,1]
	v_cvt_pk_bf16_f32 v164, v62, v63
	v_cvt_pk_bf16_f32 v165, v64, v65
	v_cvt_pk_bf16_f32 v166, v58, v59
	v_cvt_pk_bf16_f32 v167, v60, v61
	global_store_dwordx4 v230, v[164:167], s[10:11] offset:0
	v_pk_mul_f32 v[162:163], v[54:55], v[208:209] op_sel:[1,1] op_sel_hi:[0,1]
	v_pk_fma_f32 v[54:55], v[54:55], v[208:209], v[162:163] op_sel_hi:[1,0,1] neg_lo:[0,0,1]
	v_pk_mul_f32 v[162:163], v[56:57], v[210:211] op_sel:[1,1] op_sel_hi:[0,1]
	v_pk_fma_f32 v[56:57], v[56:57], v[210:211], v[162:163] op_sel_hi:[1,0,1] neg_lo:[0,0,1]
	v_pk_mul_f32 v[162:163], v[50:51], v[212:213] op_sel:[1,1] op_sel_hi:[0,1]
	v_pk_fma_f32 v[50:51], v[50:51], v[212:213], v[162:163] op_sel_hi:[1,0,1] neg_lo:[0,0,1]
	v_pk_mul_f32 v[162:163], v[52:53], v[214:215] op_sel:[1,1] op_sel_hi:[0,1]
	v_pk_fma_f32 v[52:53], v[52:53], v[214:215], v[162:163] op_sel_hi:[1,0,1] neg_lo:[0,0,1]
	v_cvt_pk_bf16_f32 v168, v54, v55
	v_cvt_pk_bf16_f32 v169, v56, v57
	v_cvt_pk_bf16_f32 v170, v50, v51
	v_cvt_pk_bf16_f32 v171, v52, v53
	global_store_dwordx4 v230, v[168:171], s[10:11] offset:256
	s_add_u32 s10, s6, 0x168000
	s_addc_u32 s11, s7, 0
	v_pk_mul_f32 v[46:47], v[46:47], v[156:157] op_sel_hi:[1,0]
	v_pk_mul_f32 v[48:49], v[48:49], v[156:157] op_sel_hi:[1,0]
	v_pk_mul_f32 v[42:43], v[42:43], v[156:157] op_sel_hi:[1,0]
	v_pk_mul_f32 v[44:45], v[44:45], v[156:157] op_sel_hi:[1,0]
	v_pk_mul_f32 v[38:39], v[38:39], v[156:157] op_sel_hi:[1,0]
	v_pk_mul_f32 v[40:41], v[40:41], v[156:157] op_sel_hi:[1,0]
	v_pk_mul_f32 v[34:35], v[34:35], v[156:157] op_sel_hi:[1,0]
	v_pk_mul_f32 v[36:37], v[36:37], v[156:157] op_sel_hi:[1,0]
	s_waitcnt vmcnt(14)
; #define GAS __attribute__((address_space(1)))
; __device__ __forceinline__ unsigned cvt_pk_bf16(float lo, float hi) { unsigned r; asm volatile("v_cvt_pk_bf16_f32 %0, %1, %2" : "=v"(r) : "v"(lo), "v"(hi)); return r; }
;     __device__ __forceinline__ void operator()(const f32x4 (&acc)[2][2][4][2], const Unit& u, int wr, int wc, int fr, int fq, const PG8_LAS float* tab) const {
;     ...
;                     f32x4 v0 = acc[ai][bj][m][0] * rs, v1 = acc[ai][bj][m][1] * rs;
;                     if (is_rope) {
;                         const GAS f32x4* rp = (const GAS f32x4*)((const GAS f32x2*)rope + (size_t)pos * 32 + ((col0 & 63) >> 1));
;                         const f32x4 cs0 = rp[0], cs1 = rp[1];
;                         f32x4 o0, o1;
;                         o0[0] = v0[0] * cs0[0] - v0[1] * cs0[1]; o0[1] = v0[1] * cs0[0] + v0[0] * cs0[1];
;                         o0[2] = v0[2] * cs0[2] - v0[3] * cs0[3]; o0[3] = v0[3] * cs0[2] + v0[2] * cs0[3];
;                         o1[0] = v1[0] * cs1[0] - v1[1] * cs1[1]; o1[1] = v1[1] * cs1[0] + v1[0] * cs1[1];
;                         o1[2] = v1[2] * cs1[2] - v1[3] * cs1[3]; o1[3] = v1[3] * cs1[2] + v1[2] * cs1[3];
;                         v0 = o0 * qs; v1 = o1 * qs;
;                     }
;                     {
;                         u32x4 w; w.x = cvt_pk_bf16(v0[0], v0[1]); w.y = cvt_pk_bf16(v0[2], v0[3]); w.z = cvt_pk_bf16(v1[0], v1[1]); w.w = cvt_pk_bf16(v1[2], v1[3]);
;                         *(GAS u32x4*)(rowp + col0) = w;
	v_pk_mul_f32 v[162:163], v[46:47], v[216:217] op_sel:[1,1] op_sel_hi:[0,1]
	v_pk_fma_f32 v[46:47], v[46:47], v[216:217], v[162:163] op_sel_hi:[1,0,1] neg_lo:[0,0,1]
	v_pk_mul_f32 v[162:163], v[48:49], v[218:219] op_sel:[1,1] op_sel_hi:[0,1]
	v_pk_fma_f32 v[48:49], v[48:49], v[218:219], v[162:163] op_sel_hi:[1,0,1] neg_lo:[0,0,1]
	v_pk_mul_f32 v[162:163], v[42:43], v[220:221] op_sel:[1,1] op_sel_hi:[0,1]
	v_pk_fma_f32 v[42:43], v[42:43], v[220:221], v[162:163] op_sel_hi:[1,0,1] neg_lo:[0,0,1]
	v_pk_mul_f32 v[162:163], v[44:45], v[222:223] op_sel:[1,1] op_sel_hi:[0,1]
	v_pk_fma_f32 v[44:45], v[44:45], v[222:223], v[162:163] op_sel_hi:[1,0,1] neg_lo:[0,0,1]
	v_cvt_pk_bf16_f32 v164, v46, v47
	v_cvt_pk_bf16_f32 v165, v48, v49
	v_cvt_pk_bf16_f32 v166, v42, v43
	v_cvt_pk_bf16_f32 v167, v44, v45
	global_store_dwordx4 v230, v[164:167], s[10:11] offset:0
	v_pk_mul_f32 v[162:163], v[38:39], v[216:217] op_sel:[1,1] op_sel_hi:[0,1]
	v_pk_fma_f32 v[38:39], v[38:39], v[216:217], v[162:163] op_sel_hi:[1,0,1] neg_lo:[0,0,1]
	v_pk_mul_f32 v[162:163], v[40:41], v[218:219] op_sel:[1,1] op_sel_hi:[0,1]
	v_pk_fma_f32 v[40:41], v[40:41], v[218:219], v[162:163] op_sel_hi:[1,0,1] neg_lo:[0,0,1]
	v_pk_mul_f32 v[162:163], v[34:35], v[220:221] op_sel:[1,1] op_sel_hi:[0,1]
	v_pk_fma_f32 v[34:35], v[34:35], v[220:221], v[162:163] op_sel_hi:[1,0,1] neg_lo:[0,0,1]
	v_pk_mul_f32 v[162:163], v[36:37], v[222:223] op_sel:[1,1] op_sel_hi:[0,1]
	v_pk_fma_f32 v[36:37], v[36:37], v[222:223], v[162:163] op_sel_hi:[1,0,1] neg_lo:[0,0,1]
	v_cvt_pk_bf16_f32 v168, v38, v39
	v_cvt_pk_bf16_f32 v169, v40, v41
	v_cvt_pk_bf16_f32 v170, v34, v35
	v_cvt_pk_bf16_f32 v171, v36, v37
	global_store_dwordx4 v230, v[168:171], s[10:11] offset:256
	s_add_u32 s10, s6, 0x190000
	s_addc_u32 s11, s7, 0
	v_pk_mul_f32 v[30:31], v[30:31], v[158:159] op_sel_hi:[1,0]
	v_pk_mul_f32 v[32:33], v[32:33], v[158:159] op_sel_hi:[1,0]
	v_pk_mul_f32 v[26:27], v[26:27], v[158:159] op_sel_hi:[1,0]
	v_pk_mul_f32 v[28:29], v[28:29], v[158:159] op_sel_hi:[1,0]
	v_pk_mul_f32 v[22:23], v[22:23], v[158:159] op_sel_hi:[1,0]
	v_pk_mul_f32 v[24:25], v[24:25], v[158:159] op_sel_hi:[1,0]
	v_pk_mul_f32 v[18:19], v[18:19], v[158:159] op_sel_hi:[1,0]
	v_pk_mul_f32 v[20:21], v[20:21], v[158:159] op_sel_hi:[1,0]
	s_waitcnt vmcnt(14)
	v_pk_mul_f32 v[162:163], v[30:31], v[224:225] op_sel:[1,1] op_sel_hi:[0,1]
	v_pk_fma_f32 v[30:31], v[30:31], v[224:225], v[162:163] op_sel_hi:[1,0,1] neg_lo:[0,0,1]
	v_pk_mul_f32 v[162:163], v[32:33], v[226:227] op_sel:[1,1] op_sel_hi:[0,1]
	v_pk_fma_f32 v[32:33], v[32:33], v[226:227], v[162:163] op_sel_hi:[1,0,1] neg_lo:[0,0,1]
	v_pk_mul_f32 v[162:163], v[26:27], v[240:241] op_sel:[1,1] op_sel_hi:[0,1]
	v_pk_fma_f32 v[26:27], v[26:27], v[240:241], v[162:163] op_sel_hi:[1,0,1] neg_lo:[0,0,1]
	v_pk_mul_f32 v[162:163], v[28:29], v[242:243] op_sel:[1,1] op_sel_hi:[0,1]
	v_pk_fma_f32 v[28:29], v[28:29], v[242:243], v[162:163] op_sel_hi:[1,0,1] neg_lo:[0,0,1]
	v_cvt_pk_bf16_f32 v164, v30, v31
	v_cvt_pk_bf16_f32 v165, v32, v33
	v_cvt_pk_bf16_f32 v166, v26, v27
	v_cvt_pk_bf16_f32 v167, v28, v29
	global_store_dwordx4 v230, v[164:167], s[10:11] offset:0
	v_pk_mul_f32 v[162:163], v[22:23], v[224:225] op_sel:[1,1] op_sel_hi:[0,1]
	v_pk_fma_f32 v[22:23], v[22:23], v[224:225], v[162:163] op_sel_hi:[1,0,1] neg_lo:[0,0,1]
	v_pk_mul_f32 v[162:163], v[24:25], v[226:227] op_sel:[1,1] op_sel_hi:[0,1]
	v_pk_fma_f32 v[24:25], v[24:25], v[226:227], v[162:163] op_sel_hi:[1,0,1] neg_lo:[0,0,1]
	v_pk_mul_f32 v[162:163], v[18:19], v[240:241] op_sel:[1,1] op_sel_hi:[0,1]
	v_pk_fma_f32 v[18:19], v[18:19], v[240:241], v[162:163] op_sel_hi:[1,0,1] neg_lo:[0,0,1]
	v_pk_mul_f32 v[162:163], v[20:21], v[242:243] op_sel:[1,1] op_sel_hi:[0,1]
	v_pk_fma_f32 v[20:21], v[20:21], v[242:243], v[162:163] op_sel_hi:[1,0,1] neg_lo:[0,0,1]
	v_cvt_pk_bf16_f32 v168, v22, v23
	v_cvt_pk_bf16_f32 v169, v24, v25
	v_cvt_pk_bf16_f32 v170, v18, v19
	v_cvt_pk_bf16_f32 v171, v20, v21
	global_store_dwordx4 v230, v[168:171], s[10:11] offset:256
	s_add_u32 s10, s6, 0x1b8000
	s_addc_u32 s11, s7, 0
	v_pk_mul_f32 v[14:15], v[14:15], v[160:161] op_sel_hi:[1,0]
	v_pk_mul_f32 v[16:17], v[16:17], v[160:161] op_sel_hi:[1,0]
	v_pk_mul_f32 v[10:11], v[10:11], v[160:161] op_sel_hi:[1,0]
	v_pk_mul_f32 v[12:13], v[12:13], v[160:161] op_sel_hi:[1,0]
	v_pk_mul_f32 v[6:7], v[6:7], v[160:161] op_sel_hi:[1,0]
	v_pk_mul_f32 v[8:9], v[8:9], v[160:161] op_sel_hi:[1,0]
	v_pk_mul_f32 v[2:3], v[2:3], v[160:161] op_sel_hi:[1,0]
	v_pk_mul_f32 v[4:5], v[4:5], v[160:161] op_sel_hi:[1,0]
	s_waitcnt vmcnt(14)
	v_pk_mul_f32 v[162:163], v[14:15], v[244:245] op_sel:[1,1] op_sel_hi:[0,1]
	v_pk_fma_f32 v[14:15], v[14:15], v[244:245], v[162:163] op_sel_hi:[1,0,1] neg_lo:[0,0,1]
	v_pk_mul_f32 v[162:163], v[16:17], v[246:247] op_sel:[1,1] op_sel_hi:[0,1]
	v_pk_fma_f32 v[16:17], v[16:17], v[246:247], v[162:163] op_sel_hi:[1,0,1] neg_lo:[0,0,1]
	v_pk_mul_f32 v[162:163], v[10:11], v[248:249] op_sel:[1,1] op_sel_hi:[0,1]
	v_pk_fma_f32 v[10:11], v[10:11], v[248:249], v[162:163] op_sel_hi:[1,0,1] neg_lo:[0,0,1]
	v_pk_mul_f32 v[162:163], v[12:13], v[250:251] op_sel:[1,1] op_sel_hi:[0,1]
	v_pk_fma_f32 v[12:13], v[12:13], v[250:251], v[162:163] op_sel_hi:[1,0,1] neg_lo:[0,0,1]
	v_cvt_pk_bf16_f32 v164, v14, v15
	v_cvt_pk_bf16_f32 v165, v16, v17
	v_cvt_pk_bf16_f32 v166, v10, v11
	v_cvt_pk_bf16_f32 v167, v12, v13
	global_store_dwordx4 v230, v[164:167], s[10:11] offset:0
	v_pk_mul_f32 v[162:163], v[6:7], v[244:245] op_sel:[1,1] op_sel_hi:[0,1]
	v_pk_fma_f32 v[6:7], v[6:7], v[244:245], v[162:163] op_sel_hi:[1,0,1] neg_lo:[0,0,1]
	v_pk_mul_f32 v[162:163], v[8:9], v[246:247] op_sel:[1,1] op_sel_hi:[0,1]
	v_pk_fma_f32 v[8:9], v[8:9], v[246:247], v[162:163] op_sel_hi:[1,0,1] neg_lo:[0,0,1]
	v_pk_mul_f32 v[162:163], v[2:3], v[248:249] op_sel:[1,1] op_sel_hi:[0,1]
	v_pk_fma_f32 v[2:3], v[2:3], v[248:249], v[162:163] op_sel_hi:[1,0,1] neg_lo:[0,0,1]
	v_pk_mul_f32 v[162:163], v[4:5], v[250:251] op_sel:[1,1] op_sel_hi:[0,1]
	v_pk_fma_f32 v[4:5], v[4:5], v[250:251], v[162:163] op_sel_hi:[1,0,1] neg_lo:[0,0,1]
	v_cvt_pk_bf16_f32 v168, v6, v7
	v_cvt_pk_bf16_f32 v169, v8, v9
	v_cvt_pk_bf16_f32 v170, v2, v3
	v_cvt_pk_bf16_f32 v171, v4, v5
	global_store_dwordx4 v230, v[168:171], s[10:11] offset:256
	s_branch .LBB0_406
